# weight conversion phase: odd waves start ~3us later so the load bursts of neighbouring waves interleave (timing only)
# speedup vs baseline: 1.0019x; 1.0019x over previous
.LBB0_28:
	v_mov_b32_e32 v0, v236
	s_mov_b32 s29, s77
	v_readfirstlane_b32 s0, v0
	s_ashr_i32 s14, s0, 6
	s_bitcmp1_b32 s14, 0
	s_cbranch_scc0 .Lconv_nostagger
	s_sleep 100
.Lconv_nostagger:
	s_add_i32 s3, s14, s83
	s_mov_b64 s[12:13], s[38:39]
	s_cmpk_lt_i32 s3, 0x1580
	s_cbranch_scc0 .LBB0_112
	s_load_dwordx4 s[4:7], s[12:13], 0x8
	s_load_dwordx4 s[16:19], s[12:13], 0x48
	s_mul_i32 s0, s28, 0x2204000
	s_lshl_b64 s[10:11], s[28:29], 22
	s_load_dwordx2 s[12:13], s[12:13], 0x80
	s_waitcnt lgkmcnt(0)
	s_add_u32 s0, s6, s0
	s_addc_u32 s1, s7, 0
	s_add_u32 s16, s16, s10
	s_addc_u32 s17, s17, s11
	s_add_u32 s10, s18, s10
	s_addc_u32 s11, s19, s11
	s_lshl_b64 s[6:7], s[28:29], 12
	v_and_b32_e32 v2, 31, v0
	v_bfe_u32 v3, v0, 5, 1
	v_bfe_u32 v15, v0, 3, 3
	v_lshlrev_b32_e32 v0, 3, v0
	s_add_u32 s6, s4, s6
	v_and_b32_e32 v0, 56, v0
	s_addc_u32 s7, s5, s7
	s_lshl_b32 s14, s14, 14
	v_mul_u32_u24_e32 v6, 0x84, v0
	v_lshlrev_b32_e32 v0, 1, v0
	s_add_i32 s14, s14, 0
	v_lshlrev_b32_e32 v4, 2, v2
	v_mul_u32_u24_e32 v5, 0x84, v3
	v_lshl_add_u64 v[10:11], s[12:13], 0, v[0:1]
	s_mov_b64 s[12:13], 0x1800000
	v_lshlrev_b32_e32 v0, 2, v15
	v_add3_u32 v14, s14, v4, v5
	v_lshl_add_u64 v[4:5], v[10:11], 0, s[12:13]
	v_add3_u32 v16, s14, v6, v0
	s_mov_b64 s[12:13], 0x1400000
	v_lshlrev_b32_e32 v0, 2, v3
	s_cmp_lg_u64 s[4:5], 0
	s_mov_b64 s[4:5], 0x200000
	v_or_b32_e32 v17, 8, v15
	v_or_b32_e32 v18, 16, v15
	v_or_b32_e32 v19, 24, v15
	v_lshl_add_u64 v[6:7], v[10:11], 0, s[12:13]
	v_lshl_add_u64 v[8:9], s[6:7], 0, v[0:1]
	s_cselect_b64 s[12:13], -1, 0
	v_lshl_add_u64 v[10:11], v[10:11], 0, s[4:5]
	s_lshl_b32 s18, s3, 5
	s_lshl_b32 s19, s20, 5
	s_lshl_b32 s24, s3, 1
	s_lshl_b32 s25, s20, 1
	v_add_u32_e32 v20, 0x400, v14
	v_add_u32_e32 v21, 0x800, v14
	v_add_u32_e32 v22, 0xc00, v14
	v_add_u32_e32 v23, 0x1000, v14
	v_add_u32_e32 v24, 0x1400, v14
	v_add_u32_e32 v25, 0x1800, v14
	v_add_u32_e32 v26, 0x1c00, v14
	s_branch .LBB0_32
